# ml_local conv stage: conv-weight loads batched up-front, select masks, math unchanged
# speedup vs baseline: 1.0638x; 1.0052x over previous
; __device__ __forceinline__ bf16_t f2bf(float f) { return (bf16_t)(pack2(f, 0.f) & 0xffffu); }
; __device__ __forceinline__ void ml_conv8_comp(const uint4* u, const float* wc, int ccol, int L, int pos, float* o) {
; #pragma unroll
;   for (int e = 0; e < 8; ++e) o[e] = 0.f;
; #pragma unroll
;   for (int j = 0; j < 4; ++j) {
;     const int pp = pos + j - 1;
;     const float mk = (pp >= 0 && pp < L) ? 1.f : 0.f;
;     float f[8];
;     unpack8(u[j], f);
;     const float4 w0 = *(const float4*)(wc + j * 1024 + ccol);
;     const float4 w1 = *(const float4*)(wc + j * 1024 + ccol + 4);
;     o[0] += f[0] * (w0.x * mk); o[1] += f[1] * (w0.y * mk); o[2] += f[2] * (w0.z * mk); o[3] += f[3] * (w0.w * mk);
;     o[4] += f[4] * (w1.x * mk); o[5] += f[5] * (w1.y * mk); o[6] += f[6] * (w1.z * mk); o[7] += f[7] * (w1.w * mk);
;   }
; __device__ void ml_local_tile(unsigned char* lds, const Params& p, int l, int b, int h, int n) {
;     ...
;   {
;     const int s = tid & 127, ec0 = tid >> 7;
;     const float wf = vec[6 * 128 + s], wb = vec[7 * 128 + s];
;     const float* wc = p.in[18] + (size_t)l * 4 * 1024;
; #pragma unroll
;     for (int i = 0; i < 4; ++i) {
;       const int ec = ec0 + 4 * i;
;       float k8[8];
;       ml_conv8_comp(ku[i], wc, 512 + h * 128 + ec * 8, L, p0 + s, k8);
;       float v8[8];
;       unpack8(vu[i], v8);
; #pragma unroll
;       for (int e = 0; e < 8; ++e) {
;         KT[(ec * 8 + e) * 136 + s] = f2bf(k8[e] * 0.08838834764831845f);
;         VF[(ec * 8 + e) * 136 + s] = f2bf(v8[e] * wf);
;         VB[(ec * 8 + e) * 136 + s] = f2bf(v8[e] * wb);
;       }
;     }
;   }
.LBB0_345:
	s_or_b64 exec, exec, s[8:9]
	s_movk_i32 s6, 0x88
	v_cmp_ge_i32_e32 vcc, s26, v92
	v_mul_lo_u32 v96, v82, s6
	s_add_i32 s6, 0, 0x19800
	s_and_b64 s[0:1], s[0:1], vcc
	v_cmp_gt_u32_e32 vcc, s26, v92
	s_waitcnt vmcnt(21)
	v_lshl_add_u32 v80, v86, 2, s6
	v_lshl_add_u64 v[84:85], v[84:85], 2, s[18:19]
	v_cndmask_b32_e64 v94, 0, 1.0, vcc
	v_cmp_ge_i32_e32 vcc, s26, v93
	s_waitcnt lgkmcnt(0)
	s_barrier
	ds_read2st64_b32 v[80:81], v80 offset0:12 offset1:14
	s_bitset1_b32 s96, 9
	v_ashrrev_i32_e32 v89, 6, v88
	v_and_b32_e32 v90, 15, v88
	v_bfe_u32 v91, v88, 4, 2
	v_lshlrev_b32_e32 v192, 3, v91
	v_readlane_b32 s0, v253, 38
	s_mov_b64 s[2:3], 0x1000
	v_lshl_add_u64 v[178:179], v[84:85], 0, s[2:3]
	s_mov_b64 s[2:3], 0x2000
	v_lshl_add_u64 v[180:181], v[84:85], 0, s[2:3]
	s_mov_b64 s[2:3], 0x3000
	v_lshl_add_u64 v[182:183], v[84:85], 0, s[2:3]
	global_load_dwordx4 v[114:117], v[84:85], off offset:2048
	global_load_dwordx4 v[118:121], v[84:85], off offset:2064
	global_load_dwordx4 v[122:125], v[178:179], off offset:2048
	global_load_dwordx4 v[126:129], v[178:179], off offset:2064
	global_load_dwordx4 v[130:133], v[180:181], off offset:2048
	global_load_dwordx4 v[134:137], v[180:181], off offset:2064
	global_load_dwordx4 v[138:141], v[182:183], off offset:2048
	global_load_dwordx4 v[142:145], v[182:183], off offset:2064
	global_load_dwordx4 v[146:149], v[84:85], off offset:2176
	global_load_dwordx4 v[150:153], v[84:85], off offset:2192
	global_load_dwordx4 v[154:157], v[178:179], off offset:2176
	global_load_dwordx4 v[158:161], v[178:179], off offset:2192
	global_load_dwordx4 v[162:165], v[180:181], off offset:2176
	global_load_dwordx4 v[166:169], v[180:181], off offset:2192
	global_load_dwordx4 v[170:173], v[182:183], off offset:2176
	global_load_dwordx4 v[174:177], v[182:183], off offset:2192
	v_add_u32_e32 v93, 1, v92
	v_add_u32_e32 v97, 2, v92
	v_cmp_lt_i32_e64 s[4:5], 0, v92
	v_cmp_gt_i32_e64 s[6:7], s26, v93
	v_cmp_gt_i32_e32 vcc, s26, v97
	s_movk_i32 s1, 0x440
	v_mul_lo_u32 v106, v87, s1
	v_mov_b32_e32 v94, 1.0
	v_cndmask_b32_e64 v95, 0, 1.0, s[4:5]
	v_cndmask_b32_e64 v93, 0, 1.0, s[6:7]
	v_cndmask_b32_e64 v92, 0, 1.0, vcc
	v_add_lshl_u32 v106, v106, v86, 1
	v_add_u32_e32 v107, s0, v106
	s_waitcnt vmcnt(8) lgkmcnt(0)
	v_mul_f32_e32 v104, v95, v114
	v_lshlrev_b32_e32 v105, 16, v76
	v_fma_f32 v96, v104, v105, 0
	v_mul_f32_e32 v104, v95, v115
	v_and_b32_e32 v105, 0xffff0000, v76
	v_fma_f32 v97, v104, v105, 0
	v_mul_f32_e32 v104, v95, v116
	v_lshlrev_b32_e32 v105, 16, v77
	v_fma_f32 v98, v104, v105, 0
	v_mul_f32_e32 v104, v95, v117
	v_and_b32_e32 v105, 0xffff0000, v77
	v_fma_f32 v99, v104, v105, 0
	v_mul_f32_e32 v104, v95, v118
	v_lshlrev_b32_e32 v105, 16, v78
	v_fma_f32 v100, v104, v105, 0
	v_mul_f32_e32 v104, v95, v119
	v_and_b32_e32 v105, 0xffff0000, v78
	v_fma_f32 v101, v104, v105, 0
	v_mul_f32_e32 v104, v95, v120
	v_lshlrev_b32_e32 v105, 16, v79
	v_fma_f32 v102, v104, v105, 0
	v_mul_f32_e32 v104, v95, v121
	v_and_b32_e32 v105, 0xffff0000, v79
	v_fma_f32 v103, v104, v105, 0
	v_mul_f32_e32 v104, v94, v122
	v_lshlrev_b32_e32 v105, 16, v72
	v_fmac_f32_e32 v96, v104, v105
	v_mul_f32_e32 v104, v94, v123
	v_and_b32_e32 v105, 0xffff0000, v72
	v_fmac_f32_e32 v97, v104, v105
	v_mul_f32_e32 v104, v94, v124
	v_lshlrev_b32_e32 v105, 16, v73
	v_fmac_f32_e32 v98, v104, v105
	v_mul_f32_e32 v104, v94, v125
	v_and_b32_e32 v105, 0xffff0000, v73
	v_fmac_f32_e32 v99, v104, v105
	v_mul_f32_e32 v104, v94, v126
	v_lshlrev_b32_e32 v105, 16, v74
	v_fmac_f32_e32 v100, v104, v105
	v_mul_f32_e32 v104, v94, v127
	v_and_b32_e32 v105, 0xffff0000, v74
	v_fmac_f32_e32 v101, v104, v105
	v_mul_f32_e32 v104, v94, v128
	v_lshlrev_b32_e32 v105, 16, v75
	v_fmac_f32_e32 v102, v104, v105
	v_mul_f32_e32 v104, v94, v129
	v_and_b32_e32 v105, 0xffff0000, v75
	v_fmac_f32_e32 v103, v104, v105
	v_mul_f32_e32 v104, v93, v130
	v_lshlrev_b32_e32 v105, 16, v68
	v_fmac_f32_e32 v96, v104, v105
	v_mul_f32_e32 v104, v93, v131
	v_and_b32_e32 v105, 0xffff0000, v68
	v_fmac_f32_e32 v97, v104, v105
	v_mul_f32_e32 v104, v93, v132
	v_lshlrev_b32_e32 v105, 16, v69
	v_fmac_f32_e32 v98, v104, v105
	v_mul_f32_e32 v104, v93, v133
	v_and_b32_e32 v105, 0xffff0000, v69
	v_fmac_f32_e32 v99, v104, v105
	v_mul_f32_e32 v104, v93, v134
	v_lshlrev_b32_e32 v105, 16, v70
	v_fmac_f32_e32 v100, v104, v105
	v_mul_f32_e32 v104, v93, v135
	v_and_b32_e32 v105, 0xffff0000, v70
	v_fmac_f32_e32 v101, v104, v105
	v_mul_f32_e32 v104, v93, v136
	v_lshlrev_b32_e32 v105, 16, v71
	v_fmac_f32_e32 v102, v104, v105
	v_mul_f32_e32 v104, v93, v137
	v_and_b32_e32 v105, 0xffff0000, v71
	v_fmac_f32_e32 v103, v104, v105
	v_mul_f32_e32 v104, v92, v138
	v_lshlrev_b32_e32 v105, 16, v64
	v_fmac_f32_e32 v96, v104, v105
	v_mul_f32_e32 v104, v92, v139
	v_and_b32_e32 v105, 0xffff0000, v64
	v_fmac_f32_e32 v97, v104, v105
	v_mul_f32_e32 v104, v92, v140
	v_lshlrev_b32_e32 v105, 16, v65
	v_fmac_f32_e32 v98, v104, v105
	v_mul_f32_e32 v104, v92, v141
	v_and_b32_e32 v105, 0xffff0000, v65
	v_fmac_f32_e32 v99, v104, v105
	v_mul_f32_e32 v104, v92, v142
	v_lshlrev_b32_e32 v105, 16, v66
	v_fmac_f32_e32 v100, v104, v105
	v_mul_f32_e32 v104, v92, v143
	v_and_b32_e32 v105, 0xffff0000, v66
	v_fmac_f32_e32 v101, v104, v105
	v_mul_f32_e32 v104, v92, v144
	v_lshlrev_b32_e32 v105, 16, v67
	v_fmac_f32_e32 v102, v104, v105
	v_mul_f32_e32 v104, v92, v145
	v_and_b32_e32 v105, 0xffff0000, v67
	v_fmac_f32_e32 v103, v104, v105
	v_mul_f32_e32 v184, 0xbfb8aa3b, v96
	v_mul_f32_e32 v185, 0xbfb8aa3b, v97
	v_mul_f32_e32 v186, 0xbfb8aa3b, v98
	v_mul_f32_e32 v187, 0xbfb8aa3b, v99
	v_mul_f32_e32 v188, 0xbfb8aa3b, v100
	v_mul_f32_e32 v189, 0xbfb8aa3b, v101
; __device__ __forceinline__ bf16_t f2bf(float f) { return (bf16_t)(pack2(f, 0.f) & 0xffffu); }
; __device__ __forceinline__ float siluf(float x) { return x * frcp(1.f + fexp(-x)); }
; __device__ __forceinline__ void ml_conv8_comp(const uint4* u, const float* wc, int ccol, int L, int pos, float* o) {
;     ...
;   for (int e = 0; e < 8; ++e) o[e] = siluf(o[e]);
; }
; __device__ void ml_local_tile(unsigned char* lds, const Params& p, int l, int b, int h, int n) {
;     ...
;     for (int i = 0; i < 4; ++i) {
;       const int ec = ec0 + 4 * i;
;       float k8[8];
;       ml_conv8_comp(ku[i], wc, 512 + h * 128 + ec * 8, L, p0 + s, k8);
;       float v8[8];
;       unpack8(vu[i], v8);
; #pragma unroll
;       for (int e = 0; e < 8; ++e) {
;         KT[(ec * 8 + e) * 136 + s] = f2bf(k8[e] * 0.08838834764831845f);
;         VF[(ec * 8 + e) * 136 + s] = f2bf(v8[e] * wf);
;         VB[(ec * 8 + e) * 136 + s] = f2bf(v8[e] * wb);
;       }
;     }
	v_mul_f32_e32 v190, 0xbfb8aa3b, v102
	v_mul_f32_e32 v191, 0xbfb8aa3b, v103
	v_exp_f32_e32 v184, v184
	v_exp_f32_e32 v185, v185
	v_exp_f32_e32 v186, v186
	v_exp_f32_e32 v187, v187
	v_exp_f32_e32 v188, v188
	v_exp_f32_e32 v189, v189
	v_exp_f32_e32 v190, v190
	v_exp_f32_e32 v191, v191
	v_add_f32_e32 v184, 1.0, v184
	v_add_f32_e32 v185, 1.0, v185
	v_add_f32_e32 v186, 1.0, v186
	v_add_f32_e32 v187, 1.0, v187
	v_add_f32_e32 v188, 1.0, v188
	v_add_f32_e32 v189, 1.0, v189
	v_add_f32_e32 v190, 1.0, v190
	v_add_f32_e32 v191, 1.0, v191
	v_rcp_f32_e32 v184, v184
	v_rcp_f32_e32 v185, v185
	v_rcp_f32_e32 v186, v186
	v_rcp_f32_e32 v187, v187
	v_rcp_f32_e32 v188, v188
	v_rcp_f32_e32 v189, v189
	v_rcp_f32_e32 v190, v190
	v_rcp_f32_e32 v191, v191
	s_nop 0
	v_mul_f32_e32 v96, v96, v184
	v_mul_f32_e32 v97, v97, v185
	v_mul_f32_e32 v98, v98, v186
	v_mul_f32_e32 v99, v99, v187
	v_mul_f32_e32 v100, v100, v188
	v_mul_f32_e32 v101, v101, v189
	v_mul_f32_e32 v102, v102, v190
	v_mul_f32_e32 v103, v103, v191
	v_mul_f32_e32 v96, 0x3db504f3, v96
	v_mul_f32_e32 v97, 0x3db504f3, v97
	v_mul_f32_e32 v98, 0x3db504f3, v98
	v_mul_f32_e32 v99, 0x3db504f3, v99
	v_mul_f32_e32 v100, 0x3db504f3, v100
	v_mul_f32_e32 v101, 0x3db504f3, v101
	v_mul_f32_e32 v102, 0x3db504f3, v102
	v_mul_f32_e32 v103, 0x3db504f3, v103
	v_cvt_pk_bf16_f32 v184, v96, v96
	v_cvt_pk_bf16_f32 v185, v97, v97
	v_cvt_pk_bf16_f32 v186, v98, v98
	v_cvt_pk_bf16_f32 v187, v99, v99
	v_cvt_pk_bf16_f32 v188, v100, v100
	v_cvt_pk_bf16_f32 v189, v101, v101
	v_cvt_pk_bf16_f32 v190, v102, v102
	v_cvt_pk_bf16_f32 v191, v103, v103
	ds_write_b16 v106, v184
	ds_write_b16 v106, v185 offset:272
	ds_write_b16 v106, v186 offset:544
	ds_write_b16 v106, v187 offset:816
	ds_write_b16 v106, v188 offset:1088
	ds_write_b16 v106, v189 offset:1360
	ds_write_b16 v106, v190 offset:1632
	ds_write_b16 v106, v191 offset:1904
	v_lshlrev_b32_e32 v105, 16, v60
	v_mul_f32_e32 v104, v80, v105
	v_mul_f32_e32 v112, v81, v105
	v_cvt_pk_bf16_f32 v104, v104, v104
	v_cvt_pk_bf16_f32 v112, v112, v112
	ds_write_b16 v106, v104 offset:34816
	ds_write_b16 v107, v112
	v_and_b32_e32 v105, 0xffff0000, v60
	v_mul_f32_e32 v104, v80, v105
	v_mul_f32_e32 v112, v81, v105
	v_cvt_pk_bf16_f32 v104, v104, v104
	v_cvt_pk_bf16_f32 v112, v112, v112
	ds_write_b16 v106, v104 offset:35088
	ds_write_b16 v107, v112 offset:272
	v_lshlrev_b32_e32 v105, 16, v61
	v_mul_f32_e32 v104, v80, v105
	v_mul_f32_e32 v112, v81, v105
	v_cvt_pk_bf16_f32 v104, v104, v104
	v_cvt_pk_bf16_f32 v112, v112, v112
	ds_write_b16 v106, v104 offset:35360
	ds_write_b16 v107, v112 offset:544
	v_and_b32_e32 v105, 0xffff0000, v61
	v_mul_f32_e32 v104, v80, v105
	v_mul_f32_e32 v112, v81, v105
	v_cvt_pk_bf16_f32 v104, v104, v104
	v_cvt_pk_bf16_f32 v112, v112, v112
	ds_write_b16 v106, v104 offset:35632
	ds_write_b16 v107, v112 offset:816
	v_lshlrev_b32_e32 v105, 16, v62
	v_mul_f32_e32 v104, v80, v105
	v_mul_f32_e32 v112, v81, v105
	v_cvt_pk_bf16_f32 v104, v104, v104
	v_cvt_pk_bf16_f32 v112, v112, v112
	ds_write_b16 v106, v104 offset:35904
	ds_write_b16 v107, v112 offset:1088
	v_and_b32_e32 v105, 0xffff0000, v62
	v_mul_f32_e32 v104, v80, v105
	v_mul_f32_e32 v112, v81, v105
	v_cvt_pk_bf16_f32 v104, v104, v104
	v_cvt_pk_bf16_f32 v112, v112, v112
	ds_write_b16 v106, v104 offset:36176
	ds_write_b16 v107, v112 offset:1360
	v_lshlrev_b32_e32 v105, 16, v63
	v_mul_f32_e32 v104, v80, v105
	v_mul_f32_e32 v112, v81, v105
	v_cvt_pk_bf16_f32 v104, v104, v104
	v_cvt_pk_bf16_f32 v112, v112, v112
	ds_write_b16 v106, v104 offset:36448
	ds_write_b16 v107, v112 offset:1632
	v_and_b32_e32 v105, 0xffff0000, v63
	v_mul_f32_e32 v104, v80, v105
	v_mul_f32_e32 v112, v81, v105
	v_cvt_pk_bf16_f32 v104, v104, v104
	v_cvt_pk_bf16_f32 v112, v112, v112
	ds_write_b16 v106, v104 offset:36720
	ds_write_b16 v107, v112 offset:1904
	global_load_dwordx4 v[114:117], v[84:85], off offset:2304
	global_load_dwordx4 v[118:121], v[84:85], off offset:2320
	global_load_dwordx4 v[122:125], v[178:179], off offset:2304
	global_load_dwordx4 v[126:129], v[178:179], off offset:2320
	global_load_dwordx4 v[130:133], v[180:181], off offset:2304
	global_load_dwordx4 v[134:137], v[180:181], off offset:2320
	global_load_dwordx4 v[138:141], v[182:183], off offset:2304
	global_load_dwordx4 v[142:145], v[182:183], off offset:2320
	s_waitcnt vmcnt(8)
; __device__ __forceinline__ bf16_t f2bf(float f) { return (bf16_t)(pack2(f, 0.f) & 0xffffu); }
; __device__ __forceinline__ float siluf(float x) { return x * frcp(1.f + fexp(-x)); }
; __device__ __forceinline__ void ml_conv8_comp(const uint4* u, const float* wc, int ccol, int L, int pos, float* o) {
; #pragma unroll
;   for (int e = 0; e < 8; ++e) o[e] = 0.f;
; #pragma unroll
;   for (int j = 0; j < 4; ++j) {
;     const int pp = pos + j - 1;
;     const float mk = (pp >= 0 && pp < L) ? 1.f : 0.f;
;     float f[8];
;     unpack8(u[j], f);
;     const float4 w0 = *(const float4*)(wc + j * 1024 + ccol);
;     const float4 w1 = *(const float4*)(wc + j * 1024 + ccol + 4);
;     o[0] += f[0] * (w0.x * mk); o[1] += f[1] * (w0.y * mk); o[2] += f[2] * (w0.z * mk); o[3] += f[3] * (w0.w * mk);
;     o[4] += f[4] * (w1.x * mk); o[5] += f[5] * (w1.y * mk); o[6] += f[6] * (w1.z * mk); o[7] += f[7] * (w1.w * mk);
;   }
; #pragma unroll
;   for (int e = 0; e < 8; ++e) o[e] = siluf(o[e]);
; }
; __device__ void ml_local_tile(unsigned char* lds, const Params& p, int l, int b, int h, int n) {
;     ...
;     for (int i = 0; i < 4; ++i) {
;       const int ec = ec0 + 4 * i;
;       float k8[8];
;       ml_conv8_comp(ku[i], wc, 512 + h * 128 + ec * 8, L, p0 + s, k8);
;       float v8[8];
;       unpack8(vu[i], v8);
; #pragma unroll
;       for (int e = 0; e < 8; ++e) {
;         KT[(ec * 8 + e) * 136 + s] = f2bf(k8[e] * 0.08838834764831845f);
;         VF[(ec * 8 + e) * 136 + s] = f2bf(v8[e] * wf);
;         VB[(ec * 8 + e) * 136 + s] = f2bf(v8[e] * wb);
;       }
;     }
	v_mul_f32_e32 v104, v95, v146
	v_lshlrev_b32_e32 v105, 16, v56
	v_fma_f32 v96, v104, v105, 0
	v_mul_f32_e32 v104, v95, v147
	v_and_b32_e32 v105, 0xffff0000, v56
	v_fma_f32 v97, v104, v105, 0
	v_mul_f32_e32 v104, v95, v148
	v_lshlrev_b32_e32 v105, 16, v57
	v_fma_f32 v98, v104, v105, 0
	v_mul_f32_e32 v104, v95, v149
	v_and_b32_e32 v105, 0xffff0000, v57
	v_fma_f32 v99, v104, v105, 0
	v_mul_f32_e32 v104, v95, v150
	v_lshlrev_b32_e32 v105, 16, v58
	v_fma_f32 v100, v104, v105, 0
	v_mul_f32_e32 v104, v95, v151
	v_and_b32_e32 v105, 0xffff0000, v58
	v_fma_f32 v101, v104, v105, 0
	v_mul_f32_e32 v104, v95, v152
	v_lshlrev_b32_e32 v105, 16, v59
	v_fma_f32 v102, v104, v105, 0
	v_mul_f32_e32 v104, v95, v153
	v_and_b32_e32 v105, 0xffff0000, v59
	v_fma_f32 v103, v104, v105, 0
	v_mul_f32_e32 v104, v94, v154
	v_lshlrev_b32_e32 v105, 16, v52
	v_fmac_f32_e32 v96, v104, v105
	v_mul_f32_e32 v104, v94, v155
	v_and_b32_e32 v105, 0xffff0000, v52
	v_fmac_f32_e32 v97, v104, v105
	v_mul_f32_e32 v104, v94, v156
	v_lshlrev_b32_e32 v105, 16, v53
	v_fmac_f32_e32 v98, v104, v105
	v_mul_f32_e32 v104, v94, v157
	v_and_b32_e32 v105, 0xffff0000, v53
	v_fmac_f32_e32 v99, v104, v105
	v_mul_f32_e32 v104, v94, v158
	v_lshlrev_b32_e32 v105, 16, v54
	v_fmac_f32_e32 v100, v104, v105
	v_mul_f32_e32 v104, v94, v159
	v_and_b32_e32 v105, 0xffff0000, v54
	v_fmac_f32_e32 v101, v104, v105
	v_mul_f32_e32 v104, v94, v160
	v_lshlrev_b32_e32 v105, 16, v55
	v_fmac_f32_e32 v102, v104, v105
	v_mul_f32_e32 v104, v94, v161
	v_and_b32_e32 v105, 0xffff0000, v55
	v_fmac_f32_e32 v103, v104, v105
	v_mul_f32_e32 v104, v93, v162
	v_lshlrev_b32_e32 v105, 16, v48
	v_fmac_f32_e32 v96, v104, v105
	v_mul_f32_e32 v104, v93, v163
	v_and_b32_e32 v105, 0xffff0000, v48
	v_fmac_f32_e32 v97, v104, v105
	v_mul_f32_e32 v104, v93, v164
	v_lshlrev_b32_e32 v105, 16, v49
	v_fmac_f32_e32 v98, v104, v105
	v_mul_f32_e32 v104, v93, v165
	v_and_b32_e32 v105, 0xffff0000, v49
	v_fmac_f32_e32 v99, v104, v105
	v_mul_f32_e32 v104, v93, v166
	v_lshlrev_b32_e32 v105, 16, v50
	v_fmac_f32_e32 v100, v104, v105
	v_mul_f32_e32 v104, v93, v167
	v_and_b32_e32 v105, 0xffff0000, v50
	v_fmac_f32_e32 v101, v104, v105
	v_mul_f32_e32 v104, v93, v168
	v_lshlrev_b32_e32 v105, 16, v51
	v_fmac_f32_e32 v102, v104, v105
	v_mul_f32_e32 v104, v93, v169
	v_and_b32_e32 v105, 0xffff0000, v51
	v_fmac_f32_e32 v103, v104, v105
	v_mul_f32_e32 v104, v92, v170
	v_lshlrev_b32_e32 v105, 16, v44
	v_fmac_f32_e32 v96, v104, v105
	v_mul_f32_e32 v104, v92, v171
	v_and_b32_e32 v105, 0xffff0000, v44
	v_fmac_f32_e32 v97, v104, v105
	v_mul_f32_e32 v104, v92, v172
	v_lshlrev_b32_e32 v105, 16, v45
	v_fmac_f32_e32 v98, v104, v105
	v_mul_f32_e32 v104, v92, v173
	v_and_b32_e32 v105, 0xffff0000, v45
	v_fmac_f32_e32 v99, v104, v105
	v_mul_f32_e32 v104, v92, v174
	v_lshlrev_b32_e32 v105, 16, v46
	v_fmac_f32_e32 v100, v104, v105
	v_mul_f32_e32 v104, v92, v175
	v_and_b32_e32 v105, 0xffff0000, v46
	v_fmac_f32_e32 v101, v104, v105
	v_mul_f32_e32 v104, v92, v176
	v_lshlrev_b32_e32 v105, 16, v47
	v_fmac_f32_e32 v102, v104, v105
	v_mul_f32_e32 v104, v92, v177
	v_and_b32_e32 v105, 0xffff0000, v47
	v_fmac_f32_e32 v103, v104, v105
	v_mul_f32_e32 v184, 0xbfb8aa3b, v96
	v_mul_f32_e32 v185, 0xbfb8aa3b, v97
	v_mul_f32_e32 v186, 0xbfb8aa3b, v98
	v_mul_f32_e32 v187, 0xbfb8aa3b, v99
	v_mul_f32_e32 v188, 0xbfb8aa3b, v100
	v_mul_f32_e32 v189, 0xbfb8aa3b, v101
	v_mul_f32_e32 v190, 0xbfb8aa3b, v102
	v_mul_f32_e32 v191, 0xbfb8aa3b, v103
	v_exp_f32_e32 v184, v184
	v_exp_f32_e32 v185, v185
	v_exp_f32_e32 v186, v186
	v_exp_f32_e32 v187, v187
	v_exp_f32_e32 v188, v188
	v_exp_f32_e32 v189, v189
	v_exp_f32_e32 v190, v190
	v_exp_f32_e32 v191, v191
	v_add_f32_e32 v184, 1.0, v184
	v_add_f32_e32 v185, 1.0, v185
	v_add_f32_e32 v186, 1.0, v186
	v_add_f32_e32 v187, 1.0, v187
	v_add_f32_e32 v188, 1.0, v188
	v_add_f32_e32 v189, 1.0, v189
	v_add_f32_e32 v190, 1.0, v190
	v_add_f32_e32 v191, 1.0, v191
	v_rcp_f32_e32 v184, v184
	v_rcp_f32_e32 v185, v185
	v_rcp_f32_e32 v186, v186
	v_rcp_f32_e32 v187, v187
	v_rcp_f32_e32 v188, v188
	v_rcp_f32_e32 v189, v189
	v_rcp_f32_e32 v190, v190
	v_rcp_f32_e32 v191, v191
	s_nop 0
	v_mul_f32_e32 v96, v96, v184
	v_mul_f32_e32 v97, v97, v185
	v_mul_f32_e32 v98, v98, v186
	v_mul_f32_e32 v99, v99, v187
	v_mul_f32_e32 v100, v100, v188
	v_mul_f32_e32 v101, v101, v189
	v_mul_f32_e32 v102, v102, v190
	v_mul_f32_e32 v103, v103, v191
	v_mul_f32_e32 v96, 0x3db504f3, v96
	v_mul_f32_e32 v97, 0x3db504f3, v97
	v_mul_f32_e32 v98, 0x3db504f3, v98
	v_mul_f32_e32 v99, 0x3db504f3, v99
	v_mul_f32_e32 v100, 0x3db504f3, v100
	v_mul_f32_e32 v101, 0x3db504f3, v101
	v_mul_f32_e32 v102, 0x3db504f3, v102
	v_mul_f32_e32 v103, 0x3db504f3, v103
	v_cvt_pk_bf16_f32 v184, v96, v96
	v_cvt_pk_bf16_f32 v185, v97, v97
	v_cvt_pk_bf16_f32 v186, v98, v98
	v_cvt_pk_bf16_f32 v187, v99, v99
	v_cvt_pk_bf16_f32 v188, v100, v100
	v_cvt_pk_bf16_f32 v189, v101, v101
	v_cvt_pk_bf16_f32 v190, v102, v102
	v_cvt_pk_bf16_f32 v191, v103, v103
	ds_write_b16 v106, v184 offset:8704
	ds_write_b16 v106, v185 offset:8976
	ds_write_b16 v106, v186 offset:9248
	ds_write_b16 v106, v187 offset:9520
	ds_write_b16 v106, v188 offset:9792
	ds_write_b16 v106, v189 offset:10064
	ds_write_b16 v106, v190 offset:10336
	ds_write_b16 v106, v191 offset:10608
	v_lshlrev_b32_e32 v105, 16, v40
	v_mul_f32_e32 v104, v80, v105
	v_mul_f32_e32 v112, v81, v105
	v_cvt_pk_bf16_f32 v104, v104, v104
	v_cvt_pk_bf16_f32 v112, v112, v112
	ds_write_b16 v106, v104 offset:43520
	ds_write_b16 v107, v112 offset:8704
	v_and_b32_e32 v105, 0xffff0000, v40
	v_mul_f32_e32 v104, v80, v105
	v_mul_f32_e32 v112, v81, v105
	v_cvt_pk_bf16_f32 v104, v104, v104
	v_cvt_pk_bf16_f32 v112, v112, v112
; __device__ __forceinline__ bf16_t f2bf(float f) { return (bf16_t)(pack2(f, 0.f) & 0xffffu); }
; __device__ __forceinline__ void ml_conv8_comp(const uint4* u, const float* wc, int ccol, int L, int pos, float* o) {
; #pragma unroll
;   for (int e = 0; e < 8; ++e) o[e] = 0.f;
; #pragma unroll
;   for (int j = 0; j < 4; ++j) {
;     const int pp = pos + j - 1;
;     const float mk = (pp >= 0 && pp < L) ? 1.f : 0.f;
;     float f[8];
;     unpack8(u[j], f);
;     const float4 w0 = *(const float4*)(wc + j * 1024 + ccol);
;     const float4 w1 = *(const float4*)(wc + j * 1024 + ccol + 4);
;     o[0] += f[0] * (w0.x * mk); o[1] += f[1] * (w0.y * mk); o[2] += f[2] * (w0.z * mk); o[3] += f[3] * (w0.w * mk);
;     o[4] += f[4] * (w1.x * mk); o[5] += f[5] * (w1.y * mk); o[6] += f[6] * (w1.z * mk); o[7] += f[7] * (w1.w * mk);
;   }
; __device__ void ml_local_tile(unsigned char* lds, const Params& p, int l, int b, int h, int n) {
;     ...
;       ml_conv8_comp(ku[i], wc, 512 + h * 128 + ec * 8, L, p0 + s, k8);
;       float v8[8];
;       unpack8(vu[i], v8);
; #pragma unroll
;       for (int e = 0; e < 8; ++e) {
;         KT[(ec * 8 + e) * 136 + s] = f2bf(k8[e] * 0.08838834764831845f);
;         VF[(ec * 8 + e) * 136 + s] = f2bf(v8[e] * wf);
;         VB[(ec * 8 + e) * 136 + s] = f2bf(v8[e] * wb);
;       }
;     }
	ds_write_b16 v106, v104 offset:43792
	ds_write_b16 v107, v112 offset:8976
	v_lshlrev_b32_e32 v105, 16, v41
	v_mul_f32_e32 v104, v80, v105
	v_mul_f32_e32 v112, v81, v105
	v_cvt_pk_bf16_f32 v104, v104, v104
	v_cvt_pk_bf16_f32 v112, v112, v112
	ds_write_b16 v106, v104 offset:44064
	ds_write_b16 v107, v112 offset:9248
	v_and_b32_e32 v105, 0xffff0000, v41
	v_mul_f32_e32 v104, v80, v105
	v_mul_f32_e32 v112, v81, v105
	v_cvt_pk_bf16_f32 v104, v104, v104
	v_cvt_pk_bf16_f32 v112, v112, v112
	ds_write_b16 v106, v104 offset:44336
	ds_write_b16 v107, v112 offset:9520
	v_lshlrev_b32_e32 v105, 16, v42
	v_mul_f32_e32 v104, v80, v105
	v_mul_f32_e32 v112, v81, v105
	v_cvt_pk_bf16_f32 v104, v104, v104
	v_cvt_pk_bf16_f32 v112, v112, v112
	ds_write_b16 v106, v104 offset:44608
	ds_write_b16 v107, v112 offset:9792
	v_and_b32_e32 v105, 0xffff0000, v42
	v_mul_f32_e32 v104, v80, v105
	v_mul_f32_e32 v112, v81, v105
	v_cvt_pk_bf16_f32 v104, v104, v104
	v_cvt_pk_bf16_f32 v112, v112, v112
	ds_write_b16 v106, v104 offset:44880
	ds_write_b16 v107, v112 offset:10064
	v_lshlrev_b32_e32 v105, 16, v43
	v_mul_f32_e32 v104, v80, v105
	v_mul_f32_e32 v112, v81, v105
	v_cvt_pk_bf16_f32 v104, v104, v104
	v_cvt_pk_bf16_f32 v112, v112, v112
	ds_write_b16 v106, v104 offset:45152
	ds_write_b16 v107, v112 offset:10336
	v_and_b32_e32 v105, 0xffff0000, v43
	v_mul_f32_e32 v104, v80, v105
	v_mul_f32_e32 v112, v81, v105
	v_cvt_pk_bf16_f32 v104, v104, v104
	v_cvt_pk_bf16_f32 v112, v112, v112
	ds_write_b16 v106, v104 offset:45424
	ds_write_b16 v107, v112 offset:10608
	global_load_dwordx4 v[146:149], v[84:85], off offset:2432
	global_load_dwordx4 v[150:153], v[84:85], off offset:2448
	global_load_dwordx4 v[154:157], v[178:179], off offset:2432
	global_load_dwordx4 v[158:161], v[178:179], off offset:2448
	global_load_dwordx4 v[162:165], v[180:181], off offset:2432
	global_load_dwordx4 v[166:169], v[180:181], off offset:2448
	global_load_dwordx4 v[170:173], v[182:183], off offset:2432
	global_load_dwordx4 v[174:177], v[182:183], off offset:2448
	s_waitcnt vmcnt(8)
	v_mul_f32_e32 v104, v95, v114
	v_lshlrev_b32_e32 v105, 16, v36
	v_fma_f32 v96, v104, v105, 0
	v_mul_f32_e32 v104, v95, v115
	v_and_b32_e32 v105, 0xffff0000, v36
	v_fma_f32 v97, v104, v105, 0
	v_mul_f32_e32 v104, v95, v116
	v_lshlrev_b32_e32 v105, 16, v37
	v_fma_f32 v98, v104, v105, 0
	v_mul_f32_e32 v104, v95, v117
	v_and_b32_e32 v105, 0xffff0000, v37
	v_fma_f32 v99, v104, v105, 0
	v_mul_f32_e32 v104, v95, v118
	v_lshlrev_b32_e32 v105, 16, v38
	v_fma_f32 v100, v104, v105, 0
	v_mul_f32_e32 v104, v95, v119
	v_and_b32_e32 v105, 0xffff0000, v38
	v_fma_f32 v101, v104, v105, 0
	v_mul_f32_e32 v104, v95, v120
	v_lshlrev_b32_e32 v105, 16, v39
	v_fma_f32 v102, v104, v105, 0
	v_mul_f32_e32 v104, v95, v121
	v_and_b32_e32 v105, 0xffff0000, v39
	v_fma_f32 v103, v104, v105, 0
	v_mul_f32_e32 v104, v94, v122
	v_lshlrev_b32_e32 v105, 16, v32
	v_fmac_f32_e32 v96, v104, v105
	v_mul_f32_e32 v104, v94, v123
	v_and_b32_e32 v105, 0xffff0000, v32
	v_fmac_f32_e32 v97, v104, v105
	v_mul_f32_e32 v104, v94, v124
	v_lshlrev_b32_e32 v105, 16, v33
	v_fmac_f32_e32 v98, v104, v105
	v_mul_f32_e32 v104, v94, v125
	v_and_b32_e32 v105, 0xffff0000, v33
	v_fmac_f32_e32 v99, v104, v105
	v_mul_f32_e32 v104, v94, v126
	v_lshlrev_b32_e32 v105, 16, v34
	v_fmac_f32_e32 v100, v104, v105
	v_mul_f32_e32 v104, v94, v127
	v_and_b32_e32 v105, 0xffff0000, v34
	v_fmac_f32_e32 v101, v104, v105
	v_mul_f32_e32 v104, v94, v128
	v_lshlrev_b32_e32 v105, 16, v35
	v_fmac_f32_e32 v102, v104, v105
	v_mul_f32_e32 v104, v94, v129
	v_and_b32_e32 v105, 0xffff0000, v35
	v_fmac_f32_e32 v103, v104, v105
	v_mul_f32_e32 v104, v93, v130
	v_lshlrev_b32_e32 v105, 16, v28
	v_fmac_f32_e32 v96, v104, v105
	v_mul_f32_e32 v104, v93, v131
	v_and_b32_e32 v105, 0xffff0000, v28
	v_fmac_f32_e32 v97, v104, v105
	v_mul_f32_e32 v104, v93, v132
	v_lshlrev_b32_e32 v105, 16, v29
	v_fmac_f32_e32 v98, v104, v105
	v_mul_f32_e32 v104, v93, v133
	v_and_b32_e32 v105, 0xffff0000, v29
	v_fmac_f32_e32 v99, v104, v105
	v_mul_f32_e32 v104, v93, v134
	v_lshlrev_b32_e32 v105, 16, v30
	v_fmac_f32_e32 v100, v104, v105
	v_mul_f32_e32 v104, v93, v135
	v_and_b32_e32 v105, 0xffff0000, v30
	v_fmac_f32_e32 v101, v104, v105
	v_mul_f32_e32 v104, v93, v136
	v_lshlrev_b32_e32 v105, 16, v31
	v_fmac_f32_e32 v102, v104, v105
	v_mul_f32_e32 v104, v93, v137
	v_and_b32_e32 v105, 0xffff0000, v31
	v_fmac_f32_e32 v103, v104, v105
	v_mul_f32_e32 v104, v92, v138
	v_lshlrev_b32_e32 v105, 16, v24
	v_fmac_f32_e32 v96, v104, v105
	v_mul_f32_e32 v104, v92, v139
	v_and_b32_e32 v105, 0xffff0000, v24
	v_fmac_f32_e32 v97, v104, v105
	v_mul_f32_e32 v104, v92, v140
	v_lshlrev_b32_e32 v105, 16, v25
	v_fmac_f32_e32 v98, v104, v105
	v_mul_f32_e32 v104, v92, v141
	v_and_b32_e32 v105, 0xffff0000, v25
	v_fmac_f32_e32 v99, v104, v105
	v_mul_f32_e32 v104, v92, v142
	v_lshlrev_b32_e32 v105, 16, v26
	v_fmac_f32_e32 v100, v104, v105
	v_mul_f32_e32 v104, v92, v143
	v_and_b32_e32 v105, 0xffff0000, v26
	v_fmac_f32_e32 v101, v104, v105
	v_mul_f32_e32 v104, v92, v144
	v_lshlrev_b32_e32 v105, 16, v27
	v_fmac_f32_e32 v102, v104, v105
	v_mul_f32_e32 v104, v92, v145
	v_and_b32_e32 v105, 0xffff0000, v27
	v_fmac_f32_e32 v103, v104, v105
	v_mul_f32_e32 v184, 0xbfb8aa3b, v96
	v_mul_f32_e32 v185, 0xbfb8aa3b, v97
	v_mul_f32_e32 v186, 0xbfb8aa3b, v98
	v_mul_f32_e32 v187, 0xbfb8aa3b, v99
	v_mul_f32_e32 v188, 0xbfb8aa3b, v100
	v_mul_f32_e32 v189, 0xbfb8aa3b, v101
	v_mul_f32_e32 v190, 0xbfb8aa3b, v102
	v_mul_f32_e32 v191, 0xbfb8aa3b, v103
	v_exp_f32_e32 v184, v184
	v_exp_f32_e32 v185, v185
	v_exp_f32_e32 v186, v186
	v_exp_f32_e32 v187, v187
	v_exp_f32_e32 v188, v188
	v_exp_f32_e32 v189, v189
; __device__ __forceinline__ bf16_t f2bf(float f) { return (bf16_t)(pack2(f, 0.f) & 0xffffu); }
; __device__ __forceinline__ float siluf(float x) { return x * frcp(1.f + fexp(-x)); }
; __device__ __forceinline__ void ml_conv8_comp(const uint4* u, const float* wc, int ccol, int L, int pos, float* o) {
; #pragma unroll
;   for (int e = 0; e < 8; ++e) o[e] = 0.f;
; #pragma unroll
;   for (int j = 0; j < 4; ++j) {
;     const int pp = pos + j - 1;
;     const float mk = (pp >= 0 && pp < L) ? 1.f : 0.f;
;     float f[8];
;     unpack8(u[j], f);
;     const float4 w0 = *(const float4*)(wc + j * 1024 + ccol);
;     const float4 w1 = *(const float4*)(wc + j * 1024 + ccol + 4);
;     o[0] += f[0] * (w0.x * mk); o[1] += f[1] * (w0.y * mk); o[2] += f[2] * (w0.z * mk); o[3] += f[3] * (w0.w * mk);
;     o[4] += f[4] * (w1.x * mk); o[5] += f[5] * (w1.y * mk); o[6] += f[6] * (w1.z * mk); o[7] += f[7] * (w1.w * mk);
;   }
; #pragma unroll
;   for (int e = 0; e < 8; ++e) o[e] = siluf(o[e]);
; }
; __device__ void ml_local_tile(unsigned char* lds, const Params& p, int l, int b, int h, int n) {
;     ...
;     for (int i = 0; i < 4; ++i) {
;       const int ec = ec0 + 4 * i;
;       float k8[8];
;       ml_conv8_comp(ku[i], wc, 512 + h * 128 + ec * 8, L, p0 + s, k8);
;       float v8[8];
;       unpack8(vu[i], v8);
; #pragma unroll
;       for (int e = 0; e < 8; ++e) {
;         KT[(ec * 8 + e) * 136 + s] = f2bf(k8[e] * 0.08838834764831845f);
;         VF[(ec * 8 + e) * 136 + s] = f2bf(v8[e] * wf);
;         VB[(ec * 8 + e) * 136 + s] = f2bf(v8[e] * wb);
;       }
;     }
	v_exp_f32_e32 v190, v190
	v_exp_f32_e32 v191, v191
	v_add_f32_e32 v184, 1.0, v184
	v_add_f32_e32 v185, 1.0, v185
	v_add_f32_e32 v186, 1.0, v186
	v_add_f32_e32 v187, 1.0, v187
	v_add_f32_e32 v188, 1.0, v188
	v_add_f32_e32 v189, 1.0, v189
	v_add_f32_e32 v190, 1.0, v190
	v_add_f32_e32 v191, 1.0, v191
	v_rcp_f32_e32 v184, v184
	v_rcp_f32_e32 v185, v185
	v_rcp_f32_e32 v186, v186
	v_rcp_f32_e32 v187, v187
	v_rcp_f32_e32 v188, v188
	v_rcp_f32_e32 v189, v189
	v_rcp_f32_e32 v190, v190
	v_rcp_f32_e32 v191, v191
	s_nop 0
	v_mul_f32_e32 v96, v96, v184
	v_mul_f32_e32 v97, v97, v185
	v_mul_f32_e32 v98, v98, v186
	v_mul_f32_e32 v99, v99, v187
	v_mul_f32_e32 v100, v100, v188
	v_mul_f32_e32 v101, v101, v189
	v_mul_f32_e32 v102, v102, v190
	v_mul_f32_e32 v103, v103, v191
	v_mul_f32_e32 v96, 0x3db504f3, v96
	v_mul_f32_e32 v97, 0x3db504f3, v97
	v_mul_f32_e32 v98, 0x3db504f3, v98
	v_mul_f32_e32 v99, 0x3db504f3, v99
	v_mul_f32_e32 v100, 0x3db504f3, v100
	v_mul_f32_e32 v101, 0x3db504f3, v101
	v_mul_f32_e32 v102, 0x3db504f3, v102
	v_mul_f32_e32 v103, 0x3db504f3, v103
	v_cvt_pk_bf16_f32 v184, v96, v96
	v_cvt_pk_bf16_f32 v185, v97, v97
	v_cvt_pk_bf16_f32 v186, v98, v98
	v_cvt_pk_bf16_f32 v187, v99, v99
	v_cvt_pk_bf16_f32 v188, v100, v100
	v_cvt_pk_bf16_f32 v189, v101, v101
	v_cvt_pk_bf16_f32 v190, v102, v102
	v_cvt_pk_bf16_f32 v191, v103, v103
	ds_write_b16 v106, v184 offset:17408
	ds_write_b16 v106, v185 offset:17680
	ds_write_b16 v106, v186 offset:17952
	ds_write_b16 v106, v187 offset:18224
	ds_write_b16 v106, v188 offset:18496
	ds_write_b16 v106, v189 offset:18768
	ds_write_b16 v106, v190 offset:19040
	ds_write_b16 v106, v191 offset:19312
	v_lshlrev_b32_e32 v105, 16, v20
	v_mul_f32_e32 v104, v80, v105
	v_mul_f32_e32 v112, v81, v105
	v_cvt_pk_bf16_f32 v104, v104, v104
	v_cvt_pk_bf16_f32 v112, v112, v112
	ds_write_b16 v106, v104 offset:52224
	ds_write_b16 v107, v112 offset:17408
	v_and_b32_e32 v105, 0xffff0000, v20
	v_mul_f32_e32 v104, v80, v105
	v_mul_f32_e32 v112, v81, v105
	v_cvt_pk_bf16_f32 v104, v104, v104
	v_cvt_pk_bf16_f32 v112, v112, v112
	ds_write_b16 v106, v104 offset:52496
	ds_write_b16 v107, v112 offset:17680
	v_lshlrev_b32_e32 v105, 16, v21
	v_mul_f32_e32 v104, v80, v105
	v_mul_f32_e32 v112, v81, v105
	v_cvt_pk_bf16_f32 v104, v104, v104
	v_cvt_pk_bf16_f32 v112, v112, v112
	ds_write_b16 v106, v104 offset:52768
	ds_write_b16 v107, v112 offset:17952
	v_and_b32_e32 v105, 0xffff0000, v21
	v_mul_f32_e32 v104, v80, v105
	v_mul_f32_e32 v112, v81, v105
	v_cvt_pk_bf16_f32 v104, v104, v104
	v_cvt_pk_bf16_f32 v112, v112, v112
	ds_write_b16 v106, v104 offset:53040
	ds_write_b16 v107, v112 offset:18224
	v_lshlrev_b32_e32 v105, 16, v22
	v_mul_f32_e32 v104, v80, v105
	v_mul_f32_e32 v112, v81, v105
	v_cvt_pk_bf16_f32 v104, v104, v104
	v_cvt_pk_bf16_f32 v112, v112, v112
	ds_write_b16 v106, v104 offset:53312
	ds_write_b16 v107, v112 offset:18496
	v_and_b32_e32 v105, 0xffff0000, v22
	v_mul_f32_e32 v104, v80, v105
	v_mul_f32_e32 v112, v81, v105
	v_cvt_pk_bf16_f32 v104, v104, v104
	v_cvt_pk_bf16_f32 v112, v112, v112
	ds_write_b16 v106, v104 offset:53584
	ds_write_b16 v107, v112 offset:18768
	v_lshlrev_b32_e32 v105, 16, v23
	v_mul_f32_e32 v104, v80, v105
	v_mul_f32_e32 v112, v81, v105
	v_cvt_pk_bf16_f32 v104, v104, v104
	v_cvt_pk_bf16_f32 v112, v112, v112
	ds_write_b16 v106, v104 offset:53856
	ds_write_b16 v107, v112 offset:19040
	v_and_b32_e32 v105, 0xffff0000, v23
	v_mul_f32_e32 v104, v80, v105
	v_mul_f32_e32 v112, v81, v105
	v_cvt_pk_bf16_f32 v104, v104, v104
	v_cvt_pk_bf16_f32 v112, v112, v112
	ds_write_b16 v106, v104 offset:54128
	ds_write_b16 v107, v112 offset:19312
	s_waitcnt vmcnt(0)
	v_mul_f32_e32 v104, v95, v146
	v_lshlrev_b32_e32 v105, 16, v16
	v_fma_f32 v96, v104, v105, 0
	v_mul_f32_e32 v104, v95, v147
	v_and_b32_e32 v105, 0xffff0000, v16
	v_fma_f32 v97, v104, v105, 0
	v_mul_f32_e32 v104, v95, v148
	v_lshlrev_b32_e32 v105, 16, v17
	v_fma_f32 v98, v104, v105, 0
	v_mul_f32_e32 v104, v95, v149
	v_and_b32_e32 v105, 0xffff0000, v17
	v_fma_f32 v99, v104, v105, 0
	v_mul_f32_e32 v104, v95, v150
	v_lshlrev_b32_e32 v105, 16, v18
	v_fma_f32 v100, v104, v105, 0
	v_mul_f32_e32 v104, v95, v151
	v_and_b32_e32 v105, 0xffff0000, v18
	v_fma_f32 v101, v104, v105, 0
	v_mul_f32_e32 v104, v95, v152
	v_lshlrev_b32_e32 v105, 16, v19
	v_fma_f32 v102, v104, v105, 0
	v_mul_f32_e32 v104, v95, v153
	v_and_b32_e32 v105, 0xffff0000, v19
	v_fma_f32 v103, v104, v105, 0
	v_mul_f32_e32 v104, v94, v154
	v_lshlrev_b32_e32 v105, 16, v12
	v_fmac_f32_e32 v96, v104, v105
	v_mul_f32_e32 v104, v94, v155
	v_and_b32_e32 v105, 0xffff0000, v12
	v_fmac_f32_e32 v97, v104, v105
	v_mul_f32_e32 v104, v94, v156
	v_lshlrev_b32_e32 v105, 16, v13
	v_fmac_f32_e32 v98, v104, v105
	v_mul_f32_e32 v104, v94, v157
	v_and_b32_e32 v105, 0xffff0000, v13
	v_fmac_f32_e32 v99, v104, v105
	v_mul_f32_e32 v104, v94, v158
	v_lshlrev_b32_e32 v105, 16, v14
	v_fmac_f32_e32 v100, v104, v105
	v_mul_f32_e32 v104, v94, v159
	v_and_b32_e32 v105, 0xffff0000, v14
	v_fmac_f32_e32 v101, v104, v105
	v_mul_f32_e32 v104, v94, v160
	v_lshlrev_b32_e32 v105, 16, v15
	v_fmac_f32_e32 v102, v104, v105
	v_mul_f32_e32 v104, v94, v161
	v_and_b32_e32 v105, 0xffff0000, v15
	v_fmac_f32_e32 v103, v104, v105
	v_mul_f32_e32 v104, v93, v162
	v_lshlrev_b32_e32 v105, 16, v8
	v_fmac_f32_e32 v96, v104, v105
	v_mul_f32_e32 v104, v93, v163
	v_and_b32_e32 v105, 0xffff0000, v8
	v_fmac_f32_e32 v97, v104, v105
	v_mul_f32_e32 v104, v93, v164
	v_lshlrev_b32_e32 v105, 16, v9
	v_fmac_f32_e32 v98, v104, v105
	v_mul_f32_e32 v104, v93, v165
	v_and_b32_e32 v105, 0xffff0000, v9
	v_fmac_f32_e32 v99, v104, v105
	v_mul_f32_e32 v104, v93, v166
	v_lshlrev_b32_e32 v105, 16, v10
; __device__ __forceinline__ bf16_t f2bf(float f) { return (bf16_t)(pack2(f, 0.f) & 0xffffu); }
; __device__ __forceinline__ float siluf(float x) { return x * frcp(1.f + fexp(-x)); }
; __device__ __forceinline__ void ml_conv8_comp(const uint4* u, const float* wc, int ccol, int L, int pos, float* o) {
; #pragma unroll
;   for (int e = 0; e < 8; ++e) o[e] = 0.f;
; #pragma unroll
;   for (int j = 0; j < 4; ++j) {
;     const int pp = pos + j - 1;
;     const float mk = (pp >= 0 && pp < L) ? 1.f : 0.f;
;     float f[8];
;     unpack8(u[j], f);
;     const float4 w0 = *(const float4*)(wc + j * 1024 + ccol);
;     const float4 w1 = *(const float4*)(wc + j * 1024 + ccol + 4);
;     o[0] += f[0] * (w0.x * mk); o[1] += f[1] * (w0.y * mk); o[2] += f[2] * (w0.z * mk); o[3] += f[3] * (w0.w * mk);
;     o[4] += f[4] * (w1.x * mk); o[5] += f[5] * (w1.y * mk); o[6] += f[6] * (w1.z * mk); o[7] += f[7] * (w1.w * mk);
;   }
; #pragma unroll
;   for (int e = 0; e < 8; ++e) o[e] = siluf(o[e]);
; }
; __device__ void ml_local_tile(unsigned char* lds, const Params& p, int l, int b, int h, int n) {
;     ...
;     for (int i = 0; i < 4; ++i) {
;       const int ec = ec0 + 4 * i;
;       float k8[8];
;       ml_conv8_comp(ku[i], wc, 512 + h * 128 + ec * 8, L, p0 + s, k8);
;       float v8[8];
;       unpack8(vu[i], v8);
; #pragma unroll
;       for (int e = 0; e < 8; ++e) {
;         KT[(ec * 8 + e) * 136 + s] = f2bf(k8[e] * 0.08838834764831845f);
;         VF[(ec * 8 + e) * 136 + s] = f2bf(v8[e] * wf);
;         VB[(ec * 8 + e) * 136 + s] = f2bf(v8[e] * wb);
;       }
;     }
	v_fmac_f32_e32 v100, v104, v105
	v_mul_f32_e32 v104, v93, v167
	v_and_b32_e32 v105, 0xffff0000, v10
	v_fmac_f32_e32 v101, v104, v105
	v_mul_f32_e32 v104, v93, v168
	v_lshlrev_b32_e32 v105, 16, v11
	v_fmac_f32_e32 v102, v104, v105
	v_mul_f32_e32 v104, v93, v169
	v_and_b32_e32 v105, 0xffff0000, v11
	v_fmac_f32_e32 v103, v104, v105
	v_mul_f32_e32 v104, v92, v170
	v_lshlrev_b32_e32 v105, 16, v4
	v_fmac_f32_e32 v96, v104, v105
	v_mul_f32_e32 v104, v92, v171
	v_and_b32_e32 v105, 0xffff0000, v4
	v_fmac_f32_e32 v97, v104, v105
	v_mul_f32_e32 v104, v92, v172
	v_lshlrev_b32_e32 v105, 16, v5
	v_fmac_f32_e32 v98, v104, v105
	v_mul_f32_e32 v104, v92, v173
	v_and_b32_e32 v105, 0xffff0000, v5
	v_fmac_f32_e32 v99, v104, v105
	v_mul_f32_e32 v104, v92, v174
	v_lshlrev_b32_e32 v105, 16, v6
	v_fmac_f32_e32 v100, v104, v105
	v_mul_f32_e32 v104, v92, v175
	v_and_b32_e32 v105, 0xffff0000, v6
	v_fmac_f32_e32 v101, v104, v105
	v_mul_f32_e32 v104, v92, v176
	v_lshlrev_b32_e32 v105, 16, v7
	v_fmac_f32_e32 v102, v104, v105
	v_mul_f32_e32 v104, v92, v177
	v_and_b32_e32 v105, 0xffff0000, v7
	v_fmac_f32_e32 v103, v104, v105
	v_mul_f32_e32 v184, 0xbfb8aa3b, v96
	v_mul_f32_e32 v185, 0xbfb8aa3b, v97
	v_mul_f32_e32 v186, 0xbfb8aa3b, v98
	v_mul_f32_e32 v187, 0xbfb8aa3b, v99
	v_mul_f32_e32 v188, 0xbfb8aa3b, v100
	v_mul_f32_e32 v189, 0xbfb8aa3b, v101
	v_mul_f32_e32 v190, 0xbfb8aa3b, v102
	v_mul_f32_e32 v191, 0xbfb8aa3b, v103
	v_exp_f32_e32 v184, v184
	v_exp_f32_e32 v185, v185
	v_exp_f32_e32 v186, v186
	v_exp_f32_e32 v187, v187
	v_exp_f32_e32 v188, v188
	v_exp_f32_e32 v189, v189
	v_exp_f32_e32 v190, v190
	v_exp_f32_e32 v191, v191
	v_add_f32_e32 v184, 1.0, v184
	v_add_f32_e32 v185, 1.0, v185
	v_add_f32_e32 v186, 1.0, v186
	v_add_f32_e32 v187, 1.0, v187
	v_add_f32_e32 v188, 1.0, v188
	v_add_f32_e32 v189, 1.0, v189
	v_add_f32_e32 v190, 1.0, v190
	v_add_f32_e32 v191, 1.0, v191
	v_rcp_f32_e32 v184, v184
	v_rcp_f32_e32 v185, v185
	v_rcp_f32_e32 v186, v186
	v_rcp_f32_e32 v187, v187
	v_rcp_f32_e32 v188, v188
	v_rcp_f32_e32 v189, v189
	v_rcp_f32_e32 v190, v190
	v_rcp_f32_e32 v191, v191
	s_nop 0
	v_mul_f32_e32 v96, v96, v184
	v_mul_f32_e32 v97, v97, v185
	v_mul_f32_e32 v98, v98, v186
	v_mul_f32_e32 v99, v99, v187
	v_mul_f32_e32 v100, v100, v188
	v_mul_f32_e32 v101, v101, v189
	v_mul_f32_e32 v102, v102, v190
	v_mul_f32_e32 v103, v103, v191
	v_mul_f32_e32 v96, 0x3db504f3, v96
	v_mul_f32_e32 v97, 0x3db504f3, v97
	v_mul_f32_e32 v98, 0x3db504f3, v98
	v_mul_f32_e32 v99, 0x3db504f3, v99
	v_mul_f32_e32 v100, 0x3db504f3, v100
	v_mul_f32_e32 v101, 0x3db504f3, v101
	v_mul_f32_e32 v102, 0x3db504f3, v102
	v_mul_f32_e32 v103, 0x3db504f3, v103
	v_cvt_pk_bf16_f32 v184, v96, v96
	v_cvt_pk_bf16_f32 v185, v97, v97
	v_cvt_pk_bf16_f32 v186, v98, v98
	v_cvt_pk_bf16_f32 v187, v99, v99
	v_cvt_pk_bf16_f32 v188, v100, v100
	v_cvt_pk_bf16_f32 v189, v101, v101
	v_cvt_pk_bf16_f32 v190, v102, v102
	v_cvt_pk_bf16_f32 v191, v103, v103
	ds_write_b16 v106, v184 offset:26112
	ds_write_b16 v106, v185 offset:26384
	ds_write_b16 v106, v186 offset:26656
	ds_write_b16 v106, v187 offset:26928
	ds_write_b16 v106, v188 offset:27200
	ds_write_b16 v106, v189 offset:27472
	ds_write_b16 v106, v190 offset:27744
	ds_write_b16 v106, v191 offset:28016
	v_lshlrev_b32_e32 v105, 16, v0
	v_mul_f32_e32 v104, v80, v105
	v_mul_f32_e32 v112, v81, v105
	v_cvt_pk_bf16_f32 v104, v104, v104
	v_cvt_pk_bf16_f32 v112, v112, v112
	ds_write_b16 v106, v104 offset:60928
	ds_write_b16 v107, v112 offset:26112
	v_and_b32_e32 v105, 0xffff0000, v0
	v_mul_f32_e32 v104, v80, v105
	v_mul_f32_e32 v112, v81, v105
	v_cvt_pk_bf16_f32 v104, v104, v104
	v_cvt_pk_bf16_f32 v112, v112, v112
	ds_write_b16 v106, v104 offset:61200
	ds_write_b16 v107, v112 offset:26384
	v_lshlrev_b32_e32 v105, 16, v1
	v_mul_f32_e32 v104, v80, v105
	v_mul_f32_e32 v112, v81, v105
	v_cvt_pk_bf16_f32 v104, v104, v104
	v_cvt_pk_bf16_f32 v112, v112, v112
	ds_write_b16 v106, v104 offset:61472
	ds_write_b16 v107, v112 offset:26656
	v_and_b32_e32 v105, 0xffff0000, v1
	v_mul_f32_e32 v104, v80, v105
	v_mul_f32_e32 v112, v81, v105
	v_cvt_pk_bf16_f32 v104, v104, v104
	v_cvt_pk_bf16_f32 v112, v112, v112
	ds_write_b16 v106, v104 offset:61744
	ds_write_b16 v107, v112 offset:26928
	v_lshlrev_b32_e32 v105, 16, v2
	v_mul_f32_e32 v104, v80, v105
	v_mul_f32_e32 v112, v81, v105
	v_cvt_pk_bf16_f32 v104, v104, v104
	v_cvt_pk_bf16_f32 v112, v112, v112
	ds_write_b16 v106, v104 offset:62016
	ds_write_b16 v107, v112 offset:27200
	v_and_b32_e32 v105, 0xffff0000, v2
	v_mul_f32_e32 v104, v80, v105
	v_mul_f32_e32 v112, v81, v105
	v_cvt_pk_bf16_f32 v104, v104, v104
	v_cvt_pk_bf16_f32 v112, v112, v112
	ds_write_b16 v106, v104 offset:62288
	ds_write_b16 v107, v112 offset:27472
	v_lshlrev_b32_e32 v105, 16, v3
	v_mul_f32_e32 v104, v80, v105
	v_mul_f32_e32 v112, v81, v105
	v_cvt_pk_bf16_f32 v104, v104, v104
	v_cvt_pk_bf16_f32 v112, v112, v112
	ds_write_b16 v106, v104 offset:62560
	ds_write_b16 v107, v112 offset:27744
	v_and_b32_e32 v105, 0xffff0000, v3
	v_mul_f32_e32 v104, v80, v105
	v_mul_f32_e32 v112, v81, v105
	v_cvt_pk_bf16_f32 v104, v104, v104
	v_cvt_pk_bf16_f32 v112, v112, v112
	ds_write_b16 v106, v104 offset:62832
	ds_write_b16 v107, v112 offset:28016
	v_lshl_or_b32 v0, v89, 4, v90
	v_lshlrev_b32_e32 v1, 4, v91
	v_mul_lo_u32 v0, v0, s93
	v_add_u32_e32 v8, 0, v1
	v_add_u32_e32 v9, v8, v0
	v_mad_u32_u24 v8, v90, s93, v8
	s_and_b32 s2, s21, -4
	s_ashr_i32 s21, s20, 31
	s_waitcnt lgkmcnt(0)
	s_barrier
; __device__ void ml_local_tile(unsigned char* lds, const Params& p, int l, int b, int h, int n) {
;     ...
;   {
;     f32x4 accf[8], accb[8];
; #pragma unroll
;     for (int i = 0; i < 8; ++i) { accf[i] = (f32x4){0.f, 0.f, 0.f, 0.f}; accb[i] = (f32x4){0.f, 0.f, 0.f, 0.f}; }
; #pragma unroll
;     for (int ks = 0; ks < 4; ++ks) {
;       const bf16x8 bfv = ldfrag(VF + (16 * w + lr) * 136 + ks * 32 + lg * 8);
;       const bf16x8 bbv = ldfrag(VB + (16 * w + lr) * 136 + ks * 32 + lg * 8);
; #pragma unroll
;       for (int ef = 0; ef < 8; ++ef) {
;         const bf16x8 a = ldfrag(KT + (ef * 16 + lr) * 136 + ks * 32 + lg * 8);
;         accf[ef] = mfma16(a, bfv, accf[ef]);
;         accb[ef] = mfma16(a, bbv, accb[ef]);
;       }
;     }
	v_add3_u32 v78, s0, v0, v1
	ds_read_b128 v[0:3], v9 offset:34816
	ds_read_b128 v[4:7], v78
	ds_read_b128 v[10:13], v8
	ds_read_b128 v[18:21], v8 offset:4352
	ds_read_b128 v[26:29], v8 offset:8704
	ds_read_b128 v[34:37], v8 offset:13056
	ds_read_b128 v[42:45], v8 offset:17408
	ds_read_b128 v[50:53], v8 offset:21760
	ds_read_b128 v[58:61], v8 offset:26112
	ds_read_b128 v[66:69], v8 offset:30464
	s_waitcnt lgkmcnt(7)
	v_mfma_f32_16x16x32_bf16 v[14:17], v[10:13], v[0:3], 0
	s_lshl_b64 s[0:1], s[20:21], 15
	s_add_u32 s0, s82, s0
	s_addc_u32 s1, s83, s1
	v_mfma_f32_16x16x32_bf16 v[10:13], v[10:13], v[4:7], 0
	s_waitcnt lgkmcnt(6)
	v_mfma_f32_16x16x32_bf16 v[22:25], v[18:21], v[0:3], 0
	v_mfma_f32_16x16x32_bf16 v[18:21], v[18:21], v[4:7], 0
	s_waitcnt lgkmcnt(5)
	v_mfma_f32_16x16x32_bf16 v[30:33], v[26:29], v[0:3], 0
	v_mfma_f32_16x16x32_bf16 v[26:29], v[26:29], v[4:7], 0
	s_waitcnt lgkmcnt(4)
	v_mfma_f32_16x16x32_bf16 v[38:41], v[34:37], v[0:3], 0
	v_mfma_f32_16x16x32_bf16 v[34:37], v[34:37], v[4:7], 0
	s_waitcnt lgkmcnt(3)
	v_mfma_f32_16x16x32_bf16 v[46:49], v[42:45], v[0:3], 0
	v_mfma_f32_16x16x32_bf16 v[42:45], v[42:45], v[4:7], 0
	s_waitcnt lgkmcnt(2)
	v_mfma_f32_16x16x32_bf16 v[54:57], v[50:53], v[0:3], 0
	v_mfma_f32_16x16x32_bf16 v[50:53], v[50:53], v[4:7], 0
	s_waitcnt lgkmcnt(1)
	v_mfma_f32_16x16x32_bf16 v[62:65], v[58:61], v[0:3], 0
	v_mfma_f32_16x16x32_bf16 v[58:61], v[58:61], v[4:7], 0
	s_waitcnt lgkmcnt(0)
	v_mfma_f32_16x16x32_bf16 v[0:3], v[66:69], v[0:3], 0
	v_mfma_f32_16x16x32_bf16 v[4:7], v[66:69], v[4:7], 0
	ds_read_b128 v[66:69], v9 offset:34880
	ds_read_b128 v[70:73], v78 offset:64
	ds_read_b128 v[74:77], v8 offset:64
	s_waitcnt lgkmcnt(0)
	v_mfma_f32_16x16x32_bf16 v[14:17], v[74:77], v[66:69], v[14:17]
	v_mfma_f32_16x16x32_bf16 v[10:13], v[74:77], v[70:73], v[10:13]
	ds_read_b128 v[74:77], v8 offset:4416
	s_waitcnt lgkmcnt(0)
	v_mfma_f32_16x16x32_bf16 v[22:25], v[74:77], v[66:69], v[22:25]
	v_mfma_f32_16x16x32_bf16 v[18:21], v[74:77], v[70:73], v[18:21]
	ds_read_b128 v[74:77], v8 offset:8768
	s_waitcnt lgkmcnt(0)
	v_mfma_f32_16x16x32_bf16 v[30:33], v[74:77], v[66:69], v[30:33]
	v_mfma_f32_16x16x32_bf16 v[26:29], v[74:77], v[70:73], v[26:29]
	ds_read_b128 v[74:77], v8 offset:13120
	s_waitcnt lgkmcnt(0)
	v_mfma_f32_16x16x32_bf16 v[38:41], v[74:77], v[66:69], v[38:41]
	v_mfma_f32_16x16x32_bf16 v[34:37], v[74:77], v[70:73], v[34:37]
	ds_read_b128 v[74:77], v8 offset:17472
	s_waitcnt lgkmcnt(0)
	v_mfma_f32_16x16x32_bf16 v[46:49], v[74:77], v[66:69], v[46:49]
	v_mfma_f32_16x16x32_bf16 v[42:45], v[74:77], v[70:73], v[42:45]
	ds_read_b128 v[74:77], v8 offset:21824
	s_waitcnt lgkmcnt(0)
	v_mfma_f32_16x16x32_bf16 v[54:57], v[74:77], v[66:69], v[54:57]
	v_mfma_f32_16x16x32_bf16 v[50:53], v[74:77], v[70:73], v[50:53]
	ds_read_b128 v[74:77], v8 offset:26176
	s_waitcnt lgkmcnt(0)
	v_mfma_f32_16x16x32_bf16 v[62:65], v[74:77], v[66:69], v[62:65]
	v_mfma_f32_16x16x32_bf16 v[58:61], v[74:77], v[70:73], v[58:61]
	ds_read_b128 v[74:77], v8 offset:30528
	s_waitcnt lgkmcnt(0)
	v_mfma_f32_16x16x32_bf16 v[0:3], v[74:77], v[66:69], v[0:3]
	v_mfma_f32_16x16x32_bf16 v[66:69], v[74:77], v[70:73], v[4:7]
	s_nop 2
	ds_read_b128 v[4:7], v9 offset:34944
	ds_read_b128 v[70:73], v78 offset:128
	ds_read_b128 v[74:77], v8 offset:128
	s_waitcnt lgkmcnt(0)
	v_mfma_f32_16x16x32_bf16 v[14:17], v[74:77], v[4:7], v[14:17]
	v_mfma_f32_16x16x32_bf16 v[10:13], v[74:77], v[70:73], v[10:13]
	ds_read_b128 v[74:77], v8 offset:4480
	s_waitcnt lgkmcnt(0)
	v_mfma_f32_16x16x32_bf16 v[22:25], v[74:77], v[4:7], v[22:25]
	v_mfma_f32_16x16x32_bf16 v[18:21], v[74:77], v[70:73], v[18:21]
	ds_read_b128 v[74:77], v8 offset:8832
	s_waitcnt lgkmcnt(0)
	v_mfma_f32_16x16x32_bf16 v[30:33], v[74:77], v[4:7], v[30:33]
	v_mfma_f32_16x16x32_bf16 v[26:29], v[74:77], v[70:73], v[26:29]
	ds_read_b128 v[74:77], v8 offset:13184
	s_waitcnt lgkmcnt(0)
	v_mfma_f32_16x16x32_bf16 v[38:41], v[74:77], v[4:7], v[38:41]
	v_mfma_f32_16x16x32_bf16 v[34:37], v[74:77], v[70:73], v[34:37]
	ds_read_b128 v[74:77], v8 offset:17536
	s_waitcnt lgkmcnt(0)
	v_mfma_f32_16x16x32_bf16 v[46:49], v[74:77], v[4:7], v[46:49]
	v_mfma_f32_16x16x32_bf16 v[42:45], v[74:77], v[70:73], v[42:45]
	ds_read_b128 v[74:77], v8 offset:21888
	s_waitcnt lgkmcnt(0)
	v_mfma_f32_16x16x32_bf16 v[54:57], v[74:77], v[4:7], v[54:57]
	v_mfma_f32_16x16x32_bf16 v[50:53], v[74:77], v[70:73], v[50:53]
	ds_read_b128 v[74:77], v8 offset:26240
	s_waitcnt lgkmcnt(0)
; __device__ __forceinline__ int sidx(int dir, int b, int h, int n) { return ((dir * 8 + b) * 4 + h) * 18 + n; }
; __device__ void ml_local_tile(unsigned char* lds, const Params& p, int l, int b, int h, int n) {
;     ...
;     for (int ks = 0; ks < 4; ++ks) {
;       const bf16x8 bfv = ldfrag(VF + (16 * w + lr) * 136 + ks * 32 + lg * 8);
;       const bf16x8 bbv = ldfrag(VB + (16 * w + lr) * 136 + ks * 32 + lg * 8);
; #pragma unroll
;       for (int ef = 0; ef < 8; ++ef) {
;         const bf16x8 a = ldfrag(KT + (ef * 16 + lr) * 136 + ks * 32 + lg * 8);
;         accf[ef] = mfma16(a, bfv, accf[ef]);
;         accb[ef] = mfma16(a, bbv, accb[ef]);
;       }
;     }
;     bf16_t* cf = Cst + (size_t)sidx(0, b, h, n) * 16384 + (16 * w + lr) * 128;
;     bf16_t* cb = Cst + (size_t)sidx(1, b, h, n) * 16384 + (16 * w + lr) * 128;
; #pragma unroll
;     for (int ef = 0; ef < 8; ++ef) {
;       uint2 u; u.x = pack2(accf[ef][0], accf[ef][1]); u.y = pack2(accf[ef][2], accf[ef][3]);
;       *(uint2*)(cf + ef * 16 + lg * 4) = u;
;       uint2 u2; u2.x = pack2(accb[ef][0], accb[ef][1]); u2.y = pack2(accb[ef][2], accb[ef][3]);
;       *(uint2*)(cb + ef * 16 + lg * 4) = u2;
;     }
;   }
;   if (tid < 256) {
	v_mfma_f32_16x16x32_bf16 v[62:65], v[74:77], v[4:7], v[62:65]
	v_mfma_f32_16x16x32_bf16 v[58:61], v[74:77], v[70:73], v[58:61]
	ds_read_b128 v[74:77], v8 offset:30592
	s_waitcnt lgkmcnt(0)
	v_mfma_f32_16x16x32_bf16 v[4:7], v[74:77], v[4:7], v[0:3]
	v_mfma_f32_16x16x32_bf16 v[0:3], v[74:77], v[70:73], v[66:69]
	s_nop 2
	ds_read_b128 v[66:69], v9 offset:35008
	ds_read_b128 v[70:73], v78 offset:192
	ds_read_b128 v[74:77], v8 offset:192
	s_waitcnt lgkmcnt(0)
	v_mfma_f32_16x16x32_bf16 v[14:17], v[74:77], v[66:69], v[14:17]
	v_mfma_f32_16x16x32_bf16 v[10:13], v[74:77], v[70:73], v[10:13]
	ds_read_b128 v[74:77], v8 offset:4544
	s_nop 5
	v_cvt_pk_bf16_f32 v14, v14, v15
	v_cvt_pk_bf16_f32 v15, v16, v17
	s_waitcnt lgkmcnt(0)
	v_mfma_f32_16x16x32_bf16 v[22:25], v[74:77], v[66:69], v[22:25]
	v_cvt_pk_bf16_f32 v10, v10, v11
	v_cvt_pk_bf16_f32 v11, v12, v13
	v_mfma_f32_16x16x32_bf16 v[18:21], v[74:77], v[70:73], v[18:21]
	ds_read_b128 v[74:77], v8 offset:8896
	s_waitcnt lgkmcnt(0)
	v_mfma_f32_16x16x32_bf16 v[30:33], v[74:77], v[66:69], v[30:33]
	v_mfma_f32_16x16x32_bf16 v[26:29], v[74:77], v[70:73], v[26:29]
	ds_read_b128 v[74:77], v8 offset:13248
	s_waitcnt lgkmcnt(0)
	v_mfma_f32_16x16x32_bf16 v[38:41], v[74:77], v[66:69], v[38:41]
	v_mfma_f32_16x16x32_bf16 v[34:37], v[74:77], v[70:73], v[34:37]
	ds_read_b128 v[74:77], v8 offset:17600
	s_waitcnt lgkmcnt(0)
	v_mfma_f32_16x16x32_bf16 v[46:49], v[74:77], v[66:69], v[46:49]
	v_mfma_f32_16x16x32_bf16 v[42:45], v[74:77], v[70:73], v[42:45]
	ds_read_b128 v[74:77], v8 offset:21952
	s_waitcnt lgkmcnt(0)
	v_mfma_f32_16x16x32_bf16 v[54:57], v[74:77], v[66:69], v[54:57]
	v_mfma_f32_16x16x32_bf16 v[50:53], v[74:77], v[70:73], v[50:53]
	ds_read_b128 v[74:77], v8 offset:26304
	s_waitcnt lgkmcnt(0)
	v_mfma_f32_16x16x32_bf16 v[62:65], v[74:77], v[66:69], v[62:65]
	v_mfma_f32_16x16x32_bf16 v[58:61], v[74:77], v[70:73], v[58:61]
	ds_read_b128 v[74:77], v8 offset:30656
	v_lshlrev_b32_e32 v8, 7, v90
	v_lshl_or_b32 v8, v89, 11, v8
	v_ashrrev_i32_e32 v9, 31, v8
	v_lshlrev_b64 v[8:9], 1, v[8:9]
	s_waitcnt lgkmcnt(0)
	v_mfma_f32_16x16x32_bf16 v[4:7], v[74:77], v[66:69], v[4:7]
	v_lshl_add_u64 v[66:67], s[0:1], 0, v[8:9]
	s_or_b32 s0, s2, s25
	s_mul_i32 s0, s0, 18
	s_add_i32 s0, s0, s24
	s_addk_i32 s0, 0x240
	s_ashr_i32 s1, s0, 31
	s_lshl_b64 s[0:1], s[0:1], 15
	s_add_u32 s0, s82, s0
	s_addc_u32 s1, s83, s1
	v_lshl_add_u64 v[8:9], s[0:1], 0, v[8:9]
	v_lshl_add_u64 v[66:67], v[66:67], 0, v[192:193]
	v_lshl_add_u64 v[8:9], v[8:9], 0, v[192:193]
	global_store_dwordx2 v[66:67], v[14:15], off
	global_store_dwordx2 v[8:9], v[10:11], off
	v_cvt_pk_bf16_f32 v10, v22, v23
	v_cvt_pk_bf16_f32 v11, v24, v25
	global_store_dwordx2 v[66:67], v[10:11], off offset:32
	v_cvt_pk_bf16_f32 v10, v18, v19
	v_cvt_pk_bf16_f32 v11, v20, v21
	global_store_dwordx2 v[8:9], v[10:11], off offset:32
	v_cvt_pk_bf16_f32 v10, v30, v31
	v_cvt_pk_bf16_f32 v11, v32, v33
	global_store_dwordx2 v[66:67], v[10:11], off offset:64
	v_cvt_pk_bf16_f32 v10, v26, v27
	v_cvt_pk_bf16_f32 v11, v28, v29
	global_store_dwordx2 v[8:9], v[10:11], off offset:64
	v_cvt_pk_bf16_f32 v10, v38, v39
	v_cvt_pk_bf16_f32 v11, v40, v41
	global_store_dwordx2 v[66:67], v[10:11], off offset:96
	v_cvt_pk_bf16_f32 v10, v34, v35
	v_cvt_pk_bf16_f32 v11, v36, v37
	global_store_dwordx2 v[8:9], v[10:11], off offset:96
	v_cvt_pk_bf16_f32 v10, v46, v47
	v_cvt_pk_bf16_f32 v11, v48, v49
	v_mfma_f32_16x16x32_bf16 v[0:3], v[74:77], v[70:73], v[0:3]
	global_store_dwordx2 v[66:67], v[10:11], off offset:128
	v_cvt_pk_bf16_f32 v10, v42, v43
	v_cvt_pk_bf16_f32 v11, v44, v45
	global_store_dwordx2 v[8:9], v[10:11], off offset:128
	v_cvt_pk_bf16_f32 v10, v54, v55
	v_cvt_pk_bf16_f32 v11, v56, v57
	global_store_dwordx2 v[66:67], v[10:11], off offset:160
	v_cvt_pk_bf16_f32 v10, v50, v51
	v_cvt_pk_bf16_f32 v11, v52, v53
	global_store_dwordx2 v[8:9], v[10:11], off offset:160
	v_cvt_pk_bf16_f32 v10, v62, v63
	v_cvt_pk_bf16_f32 v11, v64, v65
	s_movk_i32 s0, 0x100
	global_store_dwordx2 v[66:67], v[10:11], off offset:192
	v_cvt_pk_bf16_f32 v10, v58, v59
	v_cvt_pk_bf16_f32 v11, v60, v61
	v_cvt_pk_bf16_f32 v4, v4, v5
	v_cvt_pk_bf16_f32 v5, v6, v7
	v_cvt_pk_bf16_f32 v0, v0, v1
	v_cvt_pk_bf16_f32 v1, v2, v3
	v_cmp_gt_i32_e32 vcc, s0, v88
	global_store_dwordx2 v[8:9], v[10:11], off offset:192
	global_store_dwordx2 v[66:67], v[4:5], off offset:224
	global_store_dwordx2 v[8:9], v[0:1], off offset:224
	s_and_saveexec_b64 s[0:1], vcc
	s_cbranch_execz .LBB0_321
	v_lshlrev_b32_e32 v0, 2, v88
	v_and_b32_e32 v0, 0xfffffe00, v0
	v_mad_u32_u24 v1, v86, s93, 0
	s_movk_i32 s3, 0xfe00
	v_add_u32_e32 v2, 0, v0
	v_mov_b32_e32 v0, 0
